# D epilogue v3: rs cached across units with same row block, -log2e folded into conv weights, 32-bit saddr addressing
# speedup vs baseline: 1.0209x; 1.0097x over previous
.LBB0_120:
	s_mov_b32 s100, -1
	v_readlane_b32 s30, v254, 52
	v_readlane_b32 s40, v252, 4
	s_mul_i32 s25, s30, 0x8400
	v_readlane_b32 s44, v252, 8
	s_mul_hi_i32 s1, s30, 0x8400
	v_readlane_b32 s45, v252, 9
	s_add_u32 s68, s44, s25
	v_readlane_b32 s46, v252, 10
	s_addc_u32 s69, s45, s1
	s_mul_i32 s25, s30, 0x2c00
	v_readlane_b32 s47, v252, 11
	s_mul_hi_i32 s1, s30, 0x2c00
	s_add_u32 s70, s46, s25
	s_addc_u32 s71, s47, s1
	s_mul_i32 s25, s38, 0x1c00000
	v_readlane_b32 s20, v252, 32
	s_mul_hi_i32 s1, s38, 0x1c00000
	s_add_u32 s27, s20, s25
	v_readlane_b32 s20, v252, 33
	v_readlane_b32 s31, v254, 53
	s_addc_u32 s30, s20, s1
	s_mul_i32 s33, s38, 0xfea00000
	s_mul_hi_i32 s31, s38, 0xfea00000
	s_add_u32 s94, s27, s33
	s_addc_u32 s95, s30, s31
	s_add_u32 s25, s54, s25
	s_addc_u32 s1, s55, s1
	s_mul_i32 s30, s38, 0xffea0000
	s_mul_hi_i32 s27, s38, 0xffea0000
	s_add_u32 s25, s25, s30
	s_addc_u32 s1, s1, s27
	s_add_u32 s52, s25, 0x5600000
	s_addc_u32 s53, s1, 0
	s_add_u32 s50, s25, 0x5780000
	s_addc_u32 s51, s1, 0
	v_lshrrev_b32_e32 v15, 1, v14
	s_add_u32 s92, s25, 0x5900000
	v_and_b32_e32 v15, 24, v15
	s_addc_u32 s93, s1, 0
	v_and_b32_e32 v216, 15, v14
	s_lshl_b32 s1, s10, 6
	v_lshlrev_b32_e32 v16, 1, v15
	v_lshlrev_b32_e32 v14, 2, v14
	v_writelane_b32 v254, s1, 61
	v_lshl_or_b32 v16, v216, 6, v16
	s_lshl_b32 s1, s10, 13
	v_and_b32_e32 v14, 32, v14
	v_bitop3_b32 v17, v16, s1, v14 bitop3:0xde
	s_lshl_b32 s1, s11, 5
	s_and_b32 s1, s1, 0x60
	s_add_i32 m0, s75, 0x18000
	v_lshl_add_u64 v[6:7], v[6:7], 0, s[18:19]
	s_lshl_b32 s10, s1, 7
	s_waitcnt vmcnt(4)
	s_barrier
	global_load_lds_dwordx4 v[6:7], off
	v_lshl_add_u64 v[4:5], v[4:5], 0, s[18:19]
	s_add_i32 m0, s75, 0x1a000
	s_add_i32 s31, s75, 0x8000
	s_add_i32 s34, s75, 0xa000
	v_bitop3_b32 v217, v16, s10, v14 bitop3:0xde
	global_load_lds_dwordx4 v[4:5], off
	v_lshl_add_u64 v[2:3], v[2:3], 0, s[18:19]
	s_mov_b32 m0, s31
	s_add_u32 s10, s82, 0x40080
	global_load_lds_dwordx4 v[2:3], off
	v_lshl_add_u64 v[0:1], v[0:1], 0, s[18:19]
	s_mov_b32 m0, s34
	s_addc_u32 s11, s83, 0
	global_load_lds_dwordx4 v[0:1], off
	s_add_i32 m0, s75, 0x1c000
	v_lshl_add_u64 v[0:1], s[10:11], 0, v[144:145]
	global_load_lds_dwordx4 v[0:1], off
	v_lshl_add_u64 v[0:1], s[10:11], 0, v[162:163]
	s_add_i32 m0, s75, 0x1e000
	s_ashr_i32 s30, s8, 31
	global_load_lds_dwordx4 v[0:1], off
	v_lshlrev_b32_e32 v0, 14, v8
	v_and_b32_e32 v0, 0xffff8000, v0
	v_lshl_add_u32 v0, v9, 11, v0
	v_and_b32_e32 v1, 1, v8
	v_lshl_or_b32 v0, v1, 6, v0
	v_lshl_add_u32 v164, v10, 1, v0
	v_lshlrev_b32_e32 v0, 14, v11
	s_add_u32 s60, s68, 0x2c00
	v_and_b32_e32 v0, 0xffff8000, v0
	s_waitcnt vmcnt(6)
	s_addc_u32 s61, s69, 0
	v_lshl_add_u32 v0, v12, 11, v0
	v_and_b32_e32 v1, 1, v11
	v_readlane_b32 s41, v252, 5
	v_readlane_b32 s42, v252, 6
	v_readlane_b32 s43, v252, 7
	s_add_u32 s64, s68, 0x5800
	v_lshl_or_b32 v0, v1, 6, v0
	v_readlane_b32 s48, v252, 38
	s_mov_b32 s35, 0
	v_cmp_eq_u32_e64 s[38:39], 0, v216
	v_cmp_lt_u32_e64 s[40:41], 1, v216
	v_cmp_gt_u32_e64 s[42:43], 2, v216
	v_cmp_lt_u32_e64 s[44:45], 13, v216
	v_add_u32_e32 v218, -14, v216
	s_addc_u32 s65, s69, 0
	v_or_b32_e32 v219, s1, v15
	v_mov_b32_e32 v165, v145
	v_lshl_add_u32 v166, v13, 1, v0
	v_mov_b32_e32 v167, v145
	v_add_u32_e32 v220, 0, v17
	v_readlane_b32 s49, v252, 39
	s_barrier
	s_branch .LBB0_122

.LBB0_125:
	s_add_u32 s27, s86, 0xfffc0080
	s_addc_u32 s56, s87, -1
	s_add_i32 s57, 0, 0x10000
	v_add_u32_e32 v76, s57, v217
	ds_read_b128 v[64:67], v76
	ds_read_b128 v[68:71], v76 offset:1024
	ds_read_b128 v[72:75], v76 offset:2048
	ds_read_b128 v[76:79], v76 offset:3072
	s_cmp_eq_u32 s37, 12
	s_cselect_b32 vcc_hi, s1, s56
	s_cselect_b32 vcc_lo, s10, s27
	s_cselect_b32 s83, s11, s36
	s_cselect_b32 s82, s25, s33
	v_lshl_add_u64 v[168:169], s[86:87], 0, v[164:165]
	s_add_i32 m0, s75, 0xc000
	ds_read_b128 v[80:83], v220
	ds_read_b128 v[84:87], v220 offset:1024
	ds_read_b128 v[88:91], v220 offset:2048
	ds_read_b128 v[92:95], v220 offset:3072
	ds_read_b128 v[188:191], v220 offset:4096
	ds_read_b128 v[192:195], v220 offset:5120
	ds_read_b128 v[196:199], v220 offset:6144
	ds_read_b128 v[200:203], v220 offset:7168
	global_load_lds_dwordx4 v[168:169], off
	v_lshl_add_u64 v[168:169], s[86:87], 0, v[166:167]
	s_add_i32 m0, s75, 0xe000
	s_nop 0
	global_load_lds_dwordx4 v[168:169], off
	s_waitcnt lgkmcnt(8)
	s_barrier
	s_waitcnt lgkmcnt(0)
	s_setprio 1
	s_waitcnt lgkmcnt(0)
	v_mfma_f32_16x16x32_bf16 v[146:149], v[64:67], v[80:83], v[146:149]
	v_mfma_f32_16x16x32_bf16 v[116:119], v[72:75], v[80:83], v[116:119]
	v_mfma_f32_16x16x32_bf16 v[158:161], v[64:67], v[88:91], v[158:161]
	v_mfma_f32_16x16x32_bf16 v[124:127], v[72:75], v[88:91], v[124:127]
	v_mfma_f32_16x16x32_bf16 v[154:157], v[64:67], v[188:191], v[154:157]
	v_mfma_f32_16x16x32_bf16 v[112:115], v[72:75], v[188:191], v[112:115]
	v_mfma_f32_16x16x32_bf16 v[150:153], v[64:67], v[196:199], v[150:153]
	v_mfma_f32_16x16x32_bf16 v[120:123], v[72:75], v[196:199], v[120:123]
	v_mfma_f32_16x16x32_bf16 v[146:149], v[68:71], v[84:87], v[146:149]
	v_mfma_f32_16x16x32_bf16 v[116:119], v[76:79], v[84:87], v[116:119]
	v_mfma_f32_16x16x32_bf16 v[158:161], v[68:71], v[92:95], v[158:161]
	v_mfma_f32_16x16x32_bf16 v[124:127], v[76:79], v[92:95], v[124:127]
	v_mfma_f32_16x16x32_bf16 v[154:157], v[68:71], v[192:195], v[154:157]
	v_mfma_f32_16x16x32_bf16 v[112:115], v[76:79], v[192:195], v[112:115]
	v_mfma_f32_16x16x32_bf16 v[150:153], v[68:71], v[200:203], v[150:153]
	v_mfma_f32_16x16x32_bf16 v[120:123], v[76:79], v[200:203], v[120:123]
	s_setprio 0
	s_barrier
	s_add_i32 s27, 0, 0x14000
	v_add_u32_e32 v168, s27, v217
	s_add_i32 s56, s57, s74
	ds_read_b128 v[204:207], v168
	ds_read_b128 v[222:225], v168 offset:1024
	ds_read_b128 v[228:231], v168 offset:2048
	ds_read_b128 v[232:235], v168 offset:3072
	v_lshl_add_u64 v[168:169], s[82:83], 0, v[144:145]
	s_mov_b32 m0, s56
	v_lshl_add_u64 v[176:177], s[82:83], 0, v[162:163]
	global_load_lds_dwordx4 v[168:169], off
	s_add_i32 m0, s56, 0x2000
	s_nop 0
	global_load_lds_dwordx4 v[176:177], off
	s_barrier
	s_waitcnt lgkmcnt(0)
	s_setprio 1
	s_waitcnt lgkmcnt(0)
	v_mfma_f32_16x16x32_bf16 v[140:143], v[204:207], v[80:83], v[140:143]
	v_mfma_f32_16x16x32_bf16 v[80:83], v[228:231], v[80:83], v[108:111]
	v_mfma_f32_16x16x32_bf16 v[140:143], v[222:225], v[84:87], v[140:143]
	v_mfma_f32_16x16x32_bf16 v[80:83], v[232:235], v[84:87], v[80:83]
	v_mfma_f32_16x16x32_bf16 v[84:87], v[204:207], v[88:91], v[136:139]
	v_mfma_f32_16x16x32_bf16 v[88:91], v[228:231], v[88:91], v[104:107]
	v_mfma_f32_16x16x32_bf16 v[100:103], v[228:231], v[188:191], v[100:103]
	v_mfma_f32_16x16x32_bf16 v[104:107], v[204:207], v[196:199], v[128:131]
	v_mfma_f32_16x16x32_bf16 v[96:99], v[228:231], v[196:199], v[96:99]
	v_mfma_f32_16x16x32_bf16 v[84:87], v[222:225], v[92:95], v[84:87]
	v_mfma_f32_16x16x32_bf16 v[88:91], v[232:235], v[92:95], v[88:91]
	v_mfma_f32_16x16x32_bf16 v[92:95], v[204:207], v[188:191], v[132:135]
	v_mfma_f32_16x16x32_bf16 v[100:103], v[232:235], v[192:195], v[100:103]
	v_mfma_f32_16x16x32_bf16 v[128:131], v[222:225], v[200:203], v[104:107]
	v_mfma_f32_16x16x32_bf16 v[96:99], v[232:235], v[200:203], v[96:99]
	v_mfma_f32_16x16x32_bf16 v[92:95], v[222:225], v[192:195], v[92:95]
	s_setprio 0
	s_mov_b32 m0, s75
	v_lshl_add_u64 v[240:241], vcc, 0, v[144:145]
	s_barrier
	ds_read_b128 v[104:107], v220 offset:16384
	ds_read_b128 v[108:111], v220 offset:17408
	ds_read_b128 v[132:135], v220 offset:18432
	ds_read_b128 v[136:139], v220 offset:19456
	ds_read_b128 v[188:191], v220 offset:20480
	ds_read_b128 v[192:195], v220 offset:21504
	ds_read_b128 v[196:199], v220 offset:22528
	ds_read_b128 v[200:203], v220 offset:23552
	global_load_lds_dwordx4 v[240:241], off
	v_lshl_add_u64 v[242:243], vcc, 0, v[162:163]
	s_mov_b32 m0, s85
	s_nop 0
	global_load_lds_dwordx4 v[242:243], off
	s_barrier
	s_waitcnt lgkmcnt(0)
	s_setprio 1
	s_waitcnt lgkmcnt(0)
	v_mfma_f32_16x16x32_bf16 v[48:51], v[64:67], v[104:107], v[48:51]
	v_mfma_f32_16x16x32_bf16 v[20:23], v[72:75], v[104:107], v[20:23]
	v_mfma_f32_16x16x32_bf16 v[60:63], v[64:67], v[132:135], v[60:63]
	v_mfma_f32_16x16x32_bf16 v[28:31], v[72:75], v[132:135], v[28:31]
	v_mfma_f32_16x16x32_bf16 v[56:59], v[64:67], v[188:191], v[56:59]
	v_mfma_f32_16x16x32_bf16 v[16:19], v[72:75], v[188:191], v[16:19]
	v_mfma_f32_16x16x32_bf16 v[52:55], v[64:67], v[196:199], v[52:55]
	v_mfma_f32_16x16x32_bf16 v[24:27], v[72:75], v[196:199], v[24:27]
	v_mfma_f32_16x16x32_bf16 v[48:51], v[68:71], v[108:111], v[48:51]
	v_mfma_f32_16x16x32_bf16 v[20:23], v[76:79], v[108:111], v[20:23]
	v_mfma_f32_16x16x32_bf16 v[60:63], v[68:71], v[136:139], v[60:63]
	v_mfma_f32_16x16x32_bf16 v[28:31], v[76:79], v[136:139], v[28:31]
	v_mfma_f32_16x16x32_bf16 v[56:59], v[68:71], v[192:195], v[56:59]
	v_mfma_f32_16x16x32_bf16 v[16:19], v[76:79], v[192:195], v[16:19]
	v_mfma_f32_16x16x32_bf16 v[52:55], v[68:71], v[200:203], v[52:55]
	v_mfma_f32_16x16x32_bf16 v[24:27], v[76:79], v[200:203], v[24:27]
	s_setprio 0
	s_barrier
	s_add_u32 s56, s82, 0x40000
	s_addc_u32 s57, s83, 0
	s_add_i32 s27, s27, s74
	v_lshl_add_u64 v[64:65], s[56:57], 0, v[144:145]
	s_mov_b32 m0, s27
	s_nop 0
	global_load_lds_dwordx4 v[64:65], off
	v_lshl_add_u64 v[64:65], s[56:57], 0, v[162:163]
	s_add_i32 m0, s27, 0x2000
	s_nop 0
	global_load_lds_dwordx4 v[64:65], off
	s_waitcnt vmcnt(6)
	s_barrier
	s_setprio 1
	v_mfma_f32_16x16x32_bf16 v[44:47], v[204:207], v[104:107], v[44:47]
	v_mfma_f32_16x16x32_bf16 v[12:15], v[228:231], v[104:107], v[12:15]
	v_mfma_f32_16x16x32_bf16 v[40:43], v[204:207], v[132:135], v[40:43]
	v_mfma_f32_16x16x32_bf16 v[8:11], v[228:231], v[132:135], v[8:11]
	v_mfma_f32_16x16x32_bf16 v[36:39], v[204:207], v[188:191], v[36:39]
	v_mfma_f32_16x16x32_bf16 v[4:7], v[228:231], v[188:191], v[4:7]
	v_mfma_f32_16x16x32_bf16 v[32:35], v[204:207], v[196:199], v[32:35]
	v_mfma_f32_16x16x32_bf16 v[0:3], v[228:231], v[196:199], v[0:3]
	v_mfma_f32_16x16x32_bf16 v[44:47], v[222:225], v[108:111], v[44:47]
	v_mfma_f32_16x16x32_bf16 v[12:15], v[232:235], v[108:111], v[12:15]
	v_mfma_f32_16x16x32_bf16 v[40:43], v[222:225], v[136:139], v[40:43]
	v_mfma_f32_16x16x32_bf16 v[8:11], v[232:235], v[136:139], v[8:11]
	v_mfma_f32_16x16x32_bf16 v[36:39], v[222:225], v[192:195], v[36:39]
	v_mfma_f32_16x16x32_bf16 v[4:7], v[232:235], v[192:195], v[4:7]
	v_mfma_f32_16x16x32_bf16 v[32:35], v[222:225], v[200:203], v[32:35]
	v_mfma_f32_16x16x32_bf16 v[0:3], v[232:235], v[200:203], v[0:3]
	s_setprio 0
	s_add_i32 s27, 0, 0x18000
	v_add_u32_e32 v76, s27, v217
	s_barrier
	ds_read_b128 v[64:67], v76
	ds_read_b128 v[68:71], v76 offset:1024
	ds_read_b128 v[72:75], v76 offset:2048
	ds_read_b128 v[76:79], v76 offset:3072
	s_add_u32 s56, vcc_lo, 0x40000
	s_addc_u32 s57, vcc_hi, 0
	s_mov_b32 m0, s98
	v_lshl_add_u64 v[136:137], s[56:57], 0, v[144:145]
	ds_read_b128 v[104:107], v220 offset:32768
	ds_read_b128 v[108:111], v220 offset:33792
	ds_read_b128 v[132:135], v220 offset:34816
	ds_read_b128 v[188:191], v220 offset:35840
	ds_read_b128 v[192:195], v220 offset:36864
	ds_read_b128 v[196:199], v220 offset:37888
	ds_read_b128 v[200:203], v220 offset:38912
	ds_read_b128 v[204:207], v220 offset:39936
	global_load_lds_dwordx4 v[136:137], off
	v_lshl_add_u64 v[136:137], s[56:57], 0, v[162:163]
	s_mov_b32 m0, s29
	s_nop 0
	global_load_lds_dwordx4 v[136:137], off
	s_waitcnt lgkmcnt(8)
	s_barrier
	s_waitcnt lgkmcnt(0)
	s_setprio 1
	s_waitcnt lgkmcnt(0)
	v_mfma_f32_16x16x32_bf16 v[136:139], v[64:67], v[104:107], v[146:149]
	v_mfma_f32_16x16x32_bf16 v[146:149], v[68:71], v[108:111], v[136:139]
	v_mfma_f32_16x16x32_bf16 v[136:139], v[64:67], v[132:135], v[158:161]
	v_mfma_f32_16x16x32_bf16 v[158:161], v[68:71], v[188:191], v[136:139]
	v_mfma_f32_16x16x32_bf16 v[136:139], v[64:67], v[192:195], v[154:157]
	v_mfma_f32_16x16x32_bf16 v[116:119], v[72:75], v[104:107], v[116:119]
	v_mfma_f32_16x16x32_bf16 v[124:127], v[72:75], v[132:135], v[124:127]
	v_mfma_f32_16x16x32_bf16 v[154:157], v[68:71], v[196:199], v[136:139]
	v_mfma_f32_16x16x32_bf16 v[112:115], v[72:75], v[192:195], v[112:115]
	v_mfma_f32_16x16x32_bf16 v[136:139], v[64:67], v[200:203], v[150:153]
	v_mfma_f32_16x16x32_bf16 v[120:123], v[72:75], v[200:203], v[120:123]
	v_mfma_f32_16x16x32_bf16 v[116:119], v[76:79], v[108:111], v[116:119]
	v_mfma_f32_16x16x32_bf16 v[124:127], v[76:79], v[188:191], v[124:127]
	v_mfma_f32_16x16x32_bf16 v[112:115], v[76:79], v[196:199], v[112:115]
	v_mfma_f32_16x16x32_bf16 v[150:153], v[68:71], v[204:207], v[136:139]
	v_mfma_f32_16x16x32_bf16 v[120:123], v[76:79], v[204:207], v[120:123]
	s_setprio 0
	s_barrier
	s_add_i32 s58, 0, 0x1c000
	v_add_u32_e32 v136, s58, v217
	s_add_i32 s27, s27, s74
	ds_read_b128 v[222:225], v136
	ds_read_b128 v[228:231], v136 offset:1024
	ds_read_b128 v[232:235], v136 offset:2048
	ds_read_b128 v[236:239], v136 offset:3072
	v_lshl_add_u64 v[136:137], v[168:169], 0, s[18:19]
	s_mov_b32 m0, s27
	s_nop 0
	global_load_lds_dwordx4 v[136:137], off
	v_lshl_add_u64 v[136:137], v[176:177], 0, s[18:19]
	s_add_i32 m0, s27, 0x2000
	s_nop 0
	global_load_lds_dwordx4 v[136:137], off
	s_barrier
	s_waitcnt lgkmcnt(0)
	s_setprio 1
	s_waitcnt lgkmcnt(0)
	v_mfma_f32_16x16x32_bf16 v[136:139], v[222:225], v[104:107], v[140:143]
	v_mfma_f32_16x16x32_bf16 v[80:83], v[232:235], v[104:107], v[80:83]
	v_mfma_f32_16x16x32_bf16 v[140:143], v[228:231], v[108:111], v[136:139]
	v_mfma_f32_16x16x32_bf16 v[108:111], v[236:239], v[108:111], v[80:83]
	v_mfma_f32_16x16x32_bf16 v[80:83], v[222:225], v[132:135], v[84:87]
	v_mfma_f32_16x16x32_bf16 v[136:139], v[228:231], v[188:191], v[80:83]
	v_mfma_f32_16x16x32_bf16 v[80:83], v[232:235], v[132:135], v[88:91]
	v_mfma_f32_16x16x32_bf16 v[104:107], v[236:239], v[188:191], v[80:83]
	v_mfma_f32_16x16x32_bf16 v[80:83], v[222:225], v[192:195], v[92:95]
	v_mfma_f32_16x16x32_bf16 v[132:135], v[228:231], v[196:199], v[80:83]
	v_mfma_f32_16x16x32_bf16 v[80:83], v[232:235], v[192:195], v[100:103]
	v_mfma_f32_16x16x32_bf16 v[100:103], v[236:239], v[196:199], v[80:83]
	v_mfma_f32_16x16x32_bf16 v[80:83], v[222:225], v[200:203], v[128:131]
	v_mfma_f32_16x16x32_bf16 v[128:131], v[228:231], v[204:207], v[80:83]
	v_mfma_f32_16x16x32_bf16 v[80:83], v[232:235], v[200:203], v[96:99]
	v_mfma_f32_16x16x32_bf16 v[96:99], v[236:239], v[204:207], v[80:83]
	s_setprio 0
	s_mov_b32 m0, s31
	v_lshl_add_u64 v[168:169], v[240:241], 0, s[18:19]
	s_barrier
	s_nop 2
	ds_read_b128 v[80:83], v220 offset:49152
	ds_read_b128 v[84:87], v220 offset:50176
	ds_read_b128 v[88:91], v220 offset:51200
	ds_read_b128 v[92:95], v220 offset:52224
	ds_read_b128 v[188:191], v220 offset:53248
	ds_read_b128 v[192:195], v220 offset:54272
	ds_read_b128 v[196:199], v220 offset:55296
	ds_read_b128 v[200:203], v220 offset:56320
	global_load_lds_dwordx4 v[168:169], off
	v_lshl_add_u64 v[168:169], v[242:243], 0, s[18:19]
	s_mov_b32 m0, s34
	s_nop 0
	global_load_lds_dwordx4 v[168:169], off
	s_barrier
	s_waitcnt lgkmcnt(0)
	s_setprio 1
	s_waitcnt lgkmcnt(0)
	v_mfma_f32_16x16x32_bf16 v[48:51], v[64:67], v[80:83], v[48:51]
	v_mfma_f32_16x16x32_bf16 v[20:23], v[72:75], v[80:83], v[20:23]
	v_mfma_f32_16x16x32_bf16 v[60:63], v[64:67], v[88:91], v[60:63]
	v_mfma_f32_16x16x32_bf16 v[28:31], v[72:75], v[88:91], v[28:31]
	v_mfma_f32_16x16x32_bf16 v[56:59], v[64:67], v[188:191], v[56:59]
	v_mfma_f32_16x16x32_bf16 v[16:19], v[72:75], v[188:191], v[16:19]
	v_mfma_f32_16x16x32_bf16 v[52:55], v[64:67], v[196:199], v[52:55]
	v_mfma_f32_16x16x32_bf16 v[24:27], v[72:75], v[196:199], v[24:27]
	v_mfma_f32_16x16x32_bf16 v[48:51], v[68:71], v[84:87], v[48:51]
	v_mfma_f32_16x16x32_bf16 v[20:23], v[76:79], v[84:87], v[20:23]
	v_mfma_f32_16x16x32_bf16 v[60:63], v[68:71], v[92:95], v[60:63]
	v_mfma_f32_16x16x32_bf16 v[28:31], v[76:79], v[92:95], v[28:31]
	v_mfma_f32_16x16x32_bf16 v[56:59], v[68:71], v[192:195], v[56:59]
	v_mfma_f32_16x16x32_bf16 v[16:19], v[76:79], v[192:195], v[16:19]
	v_mfma_f32_16x16x32_bf16 v[52:55], v[68:71], v[200:203], v[52:55]
	v_mfma_f32_16x16x32_bf16 v[24:27], v[76:79], v[200:203], v[24:27]
	s_setprio 0
	s_barrier
	s_add_u32 s56, s82, 0x40080
	s_addc_u32 s57, s83, 0
	s_add_i32 s27, s58, s74
	v_lshl_add_u64 v[64:65], s[56:57], 0, v[144:145]
	s_mov_b32 m0, s27
	s_nop 0
	global_load_lds_dwordx4 v[64:65], off
	v_lshl_add_u64 v[64:65], s[56:57], 0, v[162:163]
	s_add_i32 m0, s27, 0x2000
	s_nop 0
	global_load_lds_dwordx4 v[64:65], off
	s_waitcnt vmcnt(6)
	s_barrier
	s_setprio 1
	v_mfma_f32_16x16x32_bf16 v[44:47], v[222:225], v[80:83], v[44:47]
	v_mfma_f32_16x16x32_bf16 v[12:15], v[232:235], v[80:83], v[12:15]
	v_mfma_f32_16x16x32_bf16 v[40:43], v[222:225], v[88:91], v[40:43]
	v_mfma_f32_16x16x32_bf16 v[8:11], v[232:235], v[88:91], v[8:11]
	v_mfma_f32_16x16x32_bf16 v[36:39], v[222:225], v[188:191], v[36:39]
	v_mfma_f32_16x16x32_bf16 v[4:7], v[232:235], v[188:191], v[4:7]
	v_mfma_f32_16x16x32_bf16 v[32:35], v[222:225], v[196:199], v[32:35]
	v_mfma_f32_16x16x32_bf16 v[0:3], v[232:235], v[196:199], v[0:3]
	v_mfma_f32_16x16x32_bf16 v[44:47], v[228:231], v[84:87], v[44:47]
	v_mfma_f32_16x16x32_bf16 v[12:15], v[236:239], v[84:87], v[12:15]
	v_mfma_f32_16x16x32_bf16 v[40:43], v[228:231], v[92:95], v[40:43]
	v_mfma_f32_16x16x32_bf16 v[8:11], v[236:239], v[92:95], v[8:11]
	v_mfma_f32_16x16x32_bf16 v[36:39], v[228:231], v[192:195], v[36:39]
	v_mfma_f32_16x16x32_bf16 v[4:7], v[236:239], v[192:195], v[4:7]
	v_mfma_f32_16x16x32_bf16 v[32:35], v[228:231], v[200:203], v[32:35]
	v_mfma_f32_16x16x32_bf16 v[0:3], v[236:239], v[200:203], v[0:3]
	s_setprio 0
	s_add_i32 s37, s37, 2
	s_add_u32 s86, s86, 0x100
	s_addc_u32 s87, s87, 0
	s_add_u32 s33, s33, 0x100
	s_addc_u32 s36, s36, 0
	s_cmp_gt_u32 s37, 13
	s_barrier
	s_cbranch_scc0 .LBB0_125
	s_lshl_b32 s1, s84, 8
	v_readlane_b32 s10, v254, 61
	s_add_i32 s1, s1, s10
	v_or_b32_e32 v198, s1, v216
	s_add_i32 s10, s1, 0x80
	v_or_b32_e32 v168, s10, v216
	v_lshl_or_b32 v188, s0, 7, v219
	v_lshlrev_b32_e32 v190, 2, v188
	v_lshlrev_b32_e32 v189, 1, v188
	s_ashr_i32 s11, s1, 5
	s_movk_i32 s10, 0xb00
	s_movk_i32 s20, 0x1600
	s_mov_b32 s101, 0xbfb8aa3b
	s_cmp_eq_u32 s84, s100
	s_cbranch_scc1 .Ldepi_w
	v_ashrrev_i32_e32 v199, 31, v198
	v_ashrrev_i32_e32 v169, 31, v168
	v_lshl_add_u64 v[170:171], v[198:199], 3, s[48:49]
	v_lshl_add_u64 v[172:173], v[168:169], 3, s[48:49]
	global_load_dwordx2 v[176:177], v[170:171], off
	global_load_dwordx2 v[202:203], v[170:171], off offset:128
	global_load_dwordx2 v[206:207], v[170:171], off offset:256
	global_load_dwordx2 v[222:223], v[170:171], off offset:384
	global_load_dwordx2 v[200:201], v[172:173], off
	global_load_dwordx2 v[196:197], v[172:173], off offset:128
	global_load_dwordx2 v[194:195], v[172:173], off offset:256
	global_load_dwordx2 v[192:193], v[172:173], off offset:384
.Ldepi_w:
	global_load_dwordx4 v[80:83], v190, s[68:69]
	global_load_dwordx4 v[64:67], v190, s[68:69] offset:16
	global_load_dwordx4 v[88:91], v190, s[60:61]
	global_load_dwordx4 v[72:75], v190, s[60:61] offset:16
	global_load_dwordx4 v[92:95], v190, s[64:65]
	global_load_dwordx4 v[76:79], v190, s[64:65] offset:16
	global_load_dwordx4 v[84:87], v190, s[70:71]
	global_load_dwordx4 v[68:71], v190, s[70:71] offset:16
	v_cmp_eq_u32_e64 s[36:37], 15, v216
	s_cmp_eq_u32 s84, s100
	s_cbranch_scc1 .Ldepi_rs_cached
	s_waitcnt vmcnt(8)
	v_ffbh_u32_e32 v224, v177
	v_ffbh_u32_e32 v225, v203
	v_ffbh_u32_e32 v226, v207
	v_ffbh_u32_e32 v227, v223
	v_ffbh_u32_e32 v228, v201
	v_ffbh_u32_e32 v229, v197
	v_ffbh_u32_e32 v230, v195
	v_ffbh_u32_e32 v231, v193
	v_min_u32_e32 v224, 32, v224
	v_min_u32_e32 v225, 32, v225
	v_min_u32_e32 v226, 32, v226
	v_min_u32_e32 v227, 32, v227
	v_min_u32_e32 v228, 32, v228
	v_min_u32_e32 v229, 32, v229
	v_min_u32_e32 v230, 32, v230
	v_min_u32_e32 v231, 32, v231
	v_lshlrev_b64 v[176:177], v224, v[176:177]
	v_lshlrev_b64 v[202:203], v225, v[202:203]
	v_lshlrev_b64 v[206:207], v226, v[206:207]
	v_lshlrev_b64 v[222:223], v227, v[222:223]
	v_lshlrev_b64 v[200:201], v228, v[200:201]
	v_lshlrev_b64 v[196:197], v229, v[196:197]
	v_lshlrev_b64 v[194:195], v230, v[194:195]
	v_lshlrev_b64 v[192:193], v231, v[192:193]
	v_min_u32_e32 v176, 1, v176
	v_min_u32_e32 v202, 1, v202
	v_min_u32_e32 v206, 1, v206
	v_min_u32_e32 v222, 1, v222
	v_min_u32_e32 v200, 1, v200
	v_min_u32_e32 v196, 1, v196
	v_min_u32_e32 v194, 1, v194
	v_min_u32_e32 v192, 1, v192
	v_or_b32_e32 v176, v177, v176
	v_or_b32_e32 v202, v203, v202
	v_or_b32_e32 v206, v207, v206
	v_or_b32_e32 v222, v223, v222
	v_or_b32_e32 v200, v201, v200
	v_or_b32_e32 v196, v197, v196
	v_or_b32_e32 v194, v195, v194
	v_or_b32_e32 v192, v193, v192
	v_cvt_f32_u32_e32 v176, v176
	v_cvt_f32_u32_e32 v202, v202
	v_cvt_f32_u32_e32 v206, v206
	v_cvt_f32_u32_e32 v222, v222
	v_cvt_f32_u32_e32 v200, v200
	v_cvt_f32_u32_e32 v196, v196
	v_cvt_f32_u32_e32 v194, v194
	v_cvt_f32_u32_e32 v192, v192
	v_sub_u32_e32 v224, 32, v224
	v_sub_u32_e32 v225, 32, v225
	v_sub_u32_e32 v226, 32, v226
	v_sub_u32_e32 v227, 32, v227
	v_sub_u32_e32 v228, 32, v228
	v_sub_u32_e32 v229, 32, v229
	v_sub_u32_e32 v230, 32, v230
	v_sub_u32_e32 v231, 32, v231
	v_ldexp_f32 v176, v176, v224
	v_ldexp_f32 v202, v202, v225
	v_ldexp_f32 v206, v206, v226
	v_ldexp_f32 v222, v222, v227
	v_ldexp_f32 v200, v200, v228
	v_ldexp_f32 v196, v196, v229
	v_ldexp_f32 v194, v194, v230
	v_ldexp_f32 v192, v192, v231
	v_mul_f32_e32 v176, 0x35800000, v176
	v_mul_f32_e32 v202, 0x35800000, v202
	v_mul_f32_e32 v206, 0x35800000, v206
	v_mul_f32_e32 v222, 0x35800000, v222
	v_mul_f32_e32 v200, 0x35800000, v200
	v_mul_f32_e32 v196, 0x35800000, v196
	v_mul_f32_e32 v194, 0x35800000, v194
	v_mul_f32_e32 v192, 0x35800000, v192
	v_fmamk_f32 v176, v176, 0x3a800000, v210
	v_fmamk_f32 v202, v202, 0x3a800000, v210
	v_fmamk_f32 v206, v206, 0x3a800000, v210
	v_fmamk_f32 v222, v222, 0x3a800000, v210
	v_fmamk_f32 v200, v200, 0x3a800000, v210
	v_fmamk_f32 v196, v196, 0x3a800000, v210
	v_fmamk_f32 v194, v194, 0x3a800000, v210
	v_fmamk_f32 v192, v192, 0x3a800000, v210
	v_rsq_f32_e32 v244, v176
	v_rsq_f32_e32 v245, v202
	v_rsq_f32_e32 v246, v206
	v_rsq_f32_e32 v247, v222
	v_rsq_f32_e32 v248, v200
	v_rsq_f32_e32 v249, v196
	v_rsq_f32_e32 v250, v194
	v_rsq_f32_e32 v251, v192
	s_mov_b32 s100, s84
.Ldepi_rs_cached:
	v_mul_f32_e32 v146, v146, v244
	v_mul_f32_e32 v158, v158, v245
	v_mul_f32_e32 v154, v154, v246
	v_mul_f32_e32 v150, v150, v247
	v_mul_f32_e32 v147, v147, v244
	v_mul_f32_e32 v159, v159, v245
	v_mul_f32_e32 v155, v155, v246
	v_mul_f32_e32 v151, v151, v247
	v_mul_f32_e32 v148, v148, v244
	v_mul_f32_e32 v160, v160, v245
	v_mul_f32_e32 v156, v156, v246
	v_mul_f32_e32 v152, v152, v247
	v_mul_f32_e32 v149, v149, v244
	v_mul_f32_e32 v161, v161, v245
	v_mul_f32_e32 v157, v157, v246
	v_mul_f32_e32 v153, v153, v247
	v_mul_f32_e32 v116, v116, v244
	v_mul_f32_e32 v124, v124, v245
	v_mul_f32_e32 v112, v112, v246
	v_mul_f32_e32 v120, v120, v247
	v_mul_f32_e32 v117, v117, v244
	v_mul_f32_e32 v125, v125, v245
	v_mul_f32_e32 v113, v113, v246
	v_mul_f32_e32 v121, v121, v247
	v_mul_f32_e32 v118, v118, v244
	v_mul_f32_e32 v126, v126, v245
	v_mul_f32_e32 v114, v114, v246
	v_mul_f32_e32 v122, v122, v247
	v_mul_f32_e32 v119, v119, v244
	v_mul_f32_e32 v127, v127, v245
	v_mul_f32_e32 v115, v115, v246
	v_mul_f32_e32 v123, v123, v247
	v_mul_f32_e32 v48, v48, v248
	v_mul_f32_e32 v60, v60, v249
	v_mul_f32_e32 v56, v56, v250
	v_mul_f32_e32 v52, v52, v251
	v_mul_f32_e32 v49, v49, v248
	v_mul_f32_e32 v61, v61, v249
	v_mul_f32_e32 v57, v57, v250
	v_mul_f32_e32 v53, v53, v251
	v_mul_f32_e32 v50, v50, v248
	v_mul_f32_e32 v62, v62, v249
	v_mul_f32_e32 v58, v58, v250
	v_mul_f32_e32 v54, v54, v251
	v_mul_f32_e32 v51, v51, v248
	v_mul_f32_e32 v63, v63, v249
	v_mul_f32_e32 v59, v59, v250
	v_mul_f32_e32 v55, v55, v251
	v_mul_f32_e32 v20, v20, v248
	v_mul_f32_e32 v28, v28, v249
	v_mul_f32_e32 v16, v16, v250
	v_mul_f32_e32 v24, v24, v251
	v_mul_f32_e32 v21, v21, v248
	v_mul_f32_e32 v29, v29, v249
	v_mul_f32_e32 v17, v17, v250
	v_mul_f32_e32 v25, v25, v251
	v_mul_f32_e32 v22, v22, v248
	v_mul_f32_e32 v30, v30, v249
	v_mul_f32_e32 v18, v18, v250
	v_mul_f32_e32 v26, v26, v251
	v_mul_f32_e32 v23, v23, v248
	v_mul_f32_e32 v31, v31, v249
	v_mul_f32_e32 v19, v19, v250
	v_mul_f32_e32 v27, v27, v251
	s_waitcnt vmcnt(0)
	v_mul_f32_e32 v64, s101, v64
	v_mul_f32_e32 v65, s101, v65
	v_mul_f32_e32 v66, s101, v66
	v_mul_f32_e32 v67, s101, v67
	v_mul_f32_e32 v68, s101, v68
	v_mul_f32_e32 v69, s101, v69
	v_mul_f32_e32 v70, s101, v70
	v_mul_f32_e32 v71, s101, v71
	v_mul_f32_e32 v72, s101, v72
	v_mul_f32_e32 v73, s101, v73
	v_mul_f32_e32 v74, s101, v74
	v_mul_f32_e32 v75, s101, v75
	v_mul_f32_e32 v76, s101, v76
	v_mul_f32_e32 v77, s101, v77
	v_mul_f32_e32 v78, s101, v78
	v_mul_f32_e32 v79, s101, v79
	v_mul_f32_e32 v80, s101, v80
	v_mul_f32_e32 v81, s101, v81
	v_mul_f32_e32 v82, s101, v82
	v_mul_f32_e32 v83, s101, v83
	v_mul_f32_e32 v84, s101, v84
	v_mul_f32_e32 v85, s101, v85
	v_mul_f32_e32 v86, s101, v86
	v_mul_f32_e32 v87, s101, v87
	v_mul_f32_e32 v88, s101, v88
	v_mul_f32_e32 v89, s101, v89
	v_mul_f32_e32 v90, s101, v90
	v_mul_f32_e32 v91, s101, v91
	v_mul_f32_e32 v92, s101, v92
	v_mul_f32_e32 v93, s101, v93
	v_mul_f32_e32 v94, s101, v94
	v_mul_f32_e32 v95, s101, v95
	v_cndmask_b32_e64 v221, v146, 0, s[36:37]
	v_cndmask_b32_e64 v225, v146, 0, s[44:45]
	v_cndmask_b32_e64 v222, v158, v146, s[36:37]
	v_cndmask_b32_e64 v226, v158, v146, s[44:45]
	v_cndmask_b32_e64 v223, v154, v158, s[36:37]
	v_cndmask_b32_e64 v227, v154, v158, s[44:45]
	v_cndmask_b32_e64 v224, v150, v154, s[36:37]
	v_cndmask_b32_e64 v228, v150, v154, s[44:45]
	v_cndmask_b32_e64 v232, v147, 0, s[36:37]
	v_cndmask_b32_e64 v236, v147, 0, s[44:45]
	v_cndmask_b32_e64 v233, v159, v147, s[36:37]
	v_cndmask_b32_e64 v237, v159, v147, s[44:45]
	v_cndmask_b32_e64 v234, v155, v159, s[36:37]
	v_cndmask_b32_e64 v238, v155, v159, s[44:45]
	v_cndmask_b32_e64 v235, v151, v155, s[36:37]
	v_cndmask_b32_e64 v239, v151, v155, s[44:45]
	v_fma_f32 v200, v92, v146, v84
	v_fma_f32 v229, v92, v158, v84
	v_fma_f32 v230, v92, v154, v84
	v_fma_f32 v231, v92, v150, v84
	v_fma_f32 v201, v93, v147, v85
	v_fma_f32 v196, v93, v159, v85
	v_fma_f32 v197, v93, v155, v85
	v_fma_f32 v176, v93, v151, v85
	v_fmac_f32_dpp v200, v221, v88 row_ror:1 row_mask:0xf bank_mask:0xf
	v_fmac_f32_dpp v229, v222, v88 row_ror:1 row_mask:0xf bank_mask:0xf
	v_fmac_f32_dpp v230, v223, v88 row_ror:1 row_mask:0xf bank_mask:0xf
	v_fmac_f32_dpp v231, v224, v88 row_ror:1 row_mask:0xf bank_mask:0xf
	v_fmac_f32_dpp v201, v232, v89 row_ror:1 row_mask:0xf bank_mask:0xf
	v_fmac_f32_dpp v196, v233, v89 row_ror:1 row_mask:0xf bank_mask:0xf
	v_fmac_f32_dpp v197, v234, v89 row_ror:1 row_mask:0xf bank_mask:0xf
	v_fmac_f32_dpp v176, v235, v89 row_ror:1 row_mask:0xf bank_mask:0xf
	v_fmac_f32_dpp v200, v225, v80 row_ror:2 row_mask:0xf bank_mask:0xf
	v_fmac_f32_dpp v229, v226, v80 row_ror:2 row_mask:0xf bank_mask:0xf
	v_fmac_f32_dpp v230, v227, v80 row_ror:2 row_mask:0xf bank_mask:0xf
	v_fmac_f32_dpp v231, v228, v80 row_ror:2 row_mask:0xf bank_mask:0xf
	v_fmac_f32_dpp v201, v236, v81 row_ror:2 row_mask:0xf bank_mask:0xf
	v_fmac_f32_dpp v196, v237, v81 row_ror:2 row_mask:0xf bank_mask:0xf
	v_fmac_f32_dpp v197, v238, v81 row_ror:2 row_mask:0xf bank_mask:0xf
	v_fmac_f32_dpp v176, v239, v81 row_ror:2 row_mask:0xf bank_mask:0xf
	v_exp_f32_e32 v221, v200
	v_exp_f32_e32 v222, v229
	v_exp_f32_e32 v223, v230
	v_exp_f32_e32 v224, v231
	v_exp_f32_e32 v232, v201
	v_exp_f32_e32 v233, v196
	v_exp_f32_e32 v234, v197
	v_exp_f32_e32 v235, v176
	v_fma_f32 v221, v221, s101, s101
	v_fma_f32 v222, v222, s101, s101
	v_fma_f32 v223, v223, s101, s101
	v_fma_f32 v224, v224, s101, s101
	v_fma_f32 v232, v232, s101, s101
	v_fma_f32 v233, v233, s101, s101
	v_fma_f32 v234, v234, s101, s101
	v_fma_f32 v235, v235, s101, s101
	v_rcp_f32_e32 v221, v221
	v_rcp_f32_e32 v222, v222
	v_rcp_f32_e32 v223, v223
	v_rcp_f32_e32 v224, v224
	v_rcp_f32_e32 v232, v232
	v_rcp_f32_e32 v233, v233
	v_rcp_f32_e32 v234, v234
	v_rcp_f32_e32 v235, v235
	v_mul_f32_e32 v221, v200, v221
	v_mul_f32_e32 v222, v229, v222
	v_mul_f32_e32 v223, v230, v223
	v_mul_f32_e32 v224, v231, v224
	v_mul_f32_e32 v232, v201, v232
	v_mul_f32_e32 v233, v196, v233
	v_mul_f32_e32 v234, v197, v234
	v_mul_f32_e32 v235, v176, v235
	v_mul_f32_e32 v192, v140, v244
	v_mul_f32_e32 v136, v136, v245
	v_mul_f32_e32 v132, v132, v246
	v_mul_f32_e32 v128, v128, v247
	v_mul_f32_e32 v193, v141, v244
	v_mul_f32_e32 v137, v137, v245
	v_mul_f32_e32 v133, v133, v246
	v_mul_f32_e32 v129, v129, v247
	v_mul_f32_e32 v140, v221, v192
	v_mul_f32_e32 v136, v222, v136
	v_mul_f32_e32 v132, v223, v132
	v_mul_f32_e32 v128, v224, v128
	v_mul_f32_e32 v141, v232, v193
	v_mul_f32_e32 v137, v233, v137
	v_mul_f32_e32 v133, v234, v133
	v_mul_f32_e32 v129, v235, v129
	v_cndmask_b32_e64 v221, v148, 0, s[36:37]
	v_cndmask_b32_e64 v225, v148, 0, s[44:45]
	v_cndmask_b32_e64 v222, v160, v148, s[36:37]
	v_cndmask_b32_e64 v226, v160, v148, s[44:45]
	v_cndmask_b32_e64 v223, v156, v160, s[36:37]
	v_cndmask_b32_e64 v227, v156, v160, s[44:45]
	v_cndmask_b32_e64 v224, v152, v156, s[36:37]
	v_cndmask_b32_e64 v228, v152, v156, s[44:45]
	v_cndmask_b32_e64 v232, v149, 0, s[36:37]
	v_cndmask_b32_e64 v236, v149, 0, s[44:45]
	v_cndmask_b32_e64 v233, v161, v149, s[36:37]
	v_cndmask_b32_e64 v237, v161, v149, s[44:45]
	v_cndmask_b32_e64 v234, v157, v161, s[36:37]
	v_cndmask_b32_e64 v238, v157, v161, s[44:45]
	v_cndmask_b32_e64 v235, v153, v157, s[36:37]
	v_cndmask_b32_e64 v239, v153, v157, s[44:45]
	v_fma_f32 v202, v94, v148, v86
	v_fma_f32 v229, v94, v160, v86
	v_fma_f32 v230, v94, v156, v86
	v_fma_f32 v231, v94, v152, v86
	v_fma_f32 v203, v95, v149, v87
	v_fma_f32 v196, v95, v161, v87
	v_fma_f32 v197, v95, v157, v87
	v_fma_f32 v176, v95, v153, v87
	v_fmac_f32_dpp v202, v221, v90 row_ror:1 row_mask:0xf bank_mask:0xf
	v_fmac_f32_dpp v229, v222, v90 row_ror:1 row_mask:0xf bank_mask:0xf
	v_fmac_f32_dpp v230, v223, v90 row_ror:1 row_mask:0xf bank_mask:0xf
	v_fmac_f32_dpp v231, v224, v90 row_ror:1 row_mask:0xf bank_mask:0xf
	v_fmac_f32_dpp v203, v232, v91 row_ror:1 row_mask:0xf bank_mask:0xf
	v_fmac_f32_dpp v196, v233, v91 row_ror:1 row_mask:0xf bank_mask:0xf
	v_fmac_f32_dpp v197, v234, v91 row_ror:1 row_mask:0xf bank_mask:0xf
	v_fmac_f32_dpp v176, v235, v91 row_ror:1 row_mask:0xf bank_mask:0xf
	v_fmac_f32_dpp v202, v225, v82 row_ror:2 row_mask:0xf bank_mask:0xf
	v_fmac_f32_dpp v229, v226, v82 row_ror:2 row_mask:0xf bank_mask:0xf
	v_fmac_f32_dpp v230, v227, v82 row_ror:2 row_mask:0xf bank_mask:0xf
	v_fmac_f32_dpp v231, v228, v82 row_ror:2 row_mask:0xf bank_mask:0xf
	v_fmac_f32_dpp v203, v236, v83 row_ror:2 row_mask:0xf bank_mask:0xf
	v_fmac_f32_dpp v196, v237, v83 row_ror:2 row_mask:0xf bank_mask:0xf
	v_fmac_f32_dpp v197, v238, v83 row_ror:2 row_mask:0xf bank_mask:0xf
	v_fmac_f32_dpp v176, v239, v83 row_ror:2 row_mask:0xf bank_mask:0xf
	v_exp_f32_e32 v221, v202
	v_exp_f32_e32 v222, v229
	v_exp_f32_e32 v223, v230
	v_exp_f32_e32 v224, v231
	v_exp_f32_e32 v232, v203
	v_exp_f32_e32 v233, v196
	v_exp_f32_e32 v234, v197
	v_exp_f32_e32 v235, v176
	v_fma_f32 v221, v221, s101, s101
	v_fma_f32 v222, v222, s101, s101
	v_fma_f32 v223, v223, s101, s101
	v_fma_f32 v224, v224, s101, s101
	v_fma_f32 v232, v232, s101, s101
	v_fma_f32 v233, v233, s101, s101
	v_fma_f32 v234, v234, s101, s101
	v_fma_f32 v235, v235, s101, s101
	v_rcp_f32_e32 v221, v221
	v_rcp_f32_e32 v222, v222
	v_rcp_f32_e32 v223, v223
	v_rcp_f32_e32 v224, v224
	v_rcp_f32_e32 v232, v232
	v_rcp_f32_e32 v233, v233
	v_rcp_f32_e32 v234, v234
	v_rcp_f32_e32 v235, v235
	v_mul_f32_e32 v221, v202, v221
	v_mul_f32_e32 v222, v229, v222
	v_mul_f32_e32 v223, v230, v223
	v_mul_f32_e32 v224, v231, v224
	v_mul_f32_e32 v232, v203, v232
	v_mul_f32_e32 v233, v196, v233
	v_mul_f32_e32 v234, v197, v234
	v_mul_f32_e32 v235, v176, v235
	v_mul_f32_e32 v194, v142, v244
	v_mul_f32_e32 v138, v138, v245
	v_mul_f32_e32 v134, v134, v246
	v_mul_f32_e32 v130, v130, v247
	v_mul_f32_e32 v195, v143, v244
	v_mul_f32_e32 v139, v139, v245
	v_mul_f32_e32 v135, v135, v246
	v_mul_f32_e32 v131, v131, v247
	v_mul_f32_e32 v142, v221, v194
	v_mul_f32_e32 v138, v222, v138
	v_mul_f32_e32 v134, v223, v134
	v_mul_f32_e32 v130, v224, v130
	v_mul_f32_e32 v143, v232, v195
	v_mul_f32_e32 v139, v233, v139
	v_mul_f32_e32 v135, v234, v135
	v_mul_f32_e32 v131, v235, v131
	v_cndmask_b32_e64 v221, v116, 0, s[36:37]
	v_cndmask_b32_e64 v225, v116, 0, s[44:45]
	v_cndmask_b32_e64 v222, v124, v116, s[36:37]
	v_cndmask_b32_e64 v226, v124, v116, s[44:45]
	v_cndmask_b32_e64 v223, v112, v124, s[36:37]
	v_cndmask_b32_e64 v227, v112, v124, s[44:45]
	v_cndmask_b32_e64 v224, v120, v112, s[36:37]
	v_cndmask_b32_e64 v228, v120, v112, s[44:45]
	v_cndmask_b32_e64 v232, v117, 0, s[36:37]
	v_cndmask_b32_e64 v236, v117, 0, s[44:45]
	v_cndmask_b32_e64 v233, v125, v117, s[36:37]
	v_cndmask_b32_e64 v237, v125, v117, s[44:45]
	v_cndmask_b32_e64 v234, v113, v125, s[36:37]
	v_cndmask_b32_e64 v238, v113, v125, s[44:45]
	v_cndmask_b32_e64 v235, v121, v113, s[36:37]
	v_cndmask_b32_e64 v239, v121, v113, s[44:45]
	v_fma_f32 v204, v76, v116, v68
	v_fma_f32 v229, v76, v124, v68
	v_fma_f32 v230, v76, v112, v68
	v_fma_f32 v231, v76, v120, v68
	v_fma_f32 v205, v77, v117, v69
	v_fma_f32 v196, v77, v125, v69
	v_fma_f32 v197, v77, v113, v69
	v_fma_f32 v176, v77, v121, v69
	v_fmac_f32_dpp v204, v221, v72 row_ror:1 row_mask:0xf bank_mask:0xf
	v_fmac_f32_dpp v229, v222, v72 row_ror:1 row_mask:0xf bank_mask:0xf
	v_fmac_f32_dpp v230, v223, v72 row_ror:1 row_mask:0xf bank_mask:0xf
	v_fmac_f32_dpp v231, v224, v72 row_ror:1 row_mask:0xf bank_mask:0xf
	v_fmac_f32_dpp v205, v232, v73 row_ror:1 row_mask:0xf bank_mask:0xf
	v_fmac_f32_dpp v196, v233, v73 row_ror:1 row_mask:0xf bank_mask:0xf
	v_fmac_f32_dpp v197, v234, v73 row_ror:1 row_mask:0xf bank_mask:0xf
	v_fmac_f32_dpp v176, v235, v73 row_ror:1 row_mask:0xf bank_mask:0xf
	v_fmac_f32_dpp v204, v225, v64 row_ror:2 row_mask:0xf bank_mask:0xf
	v_fmac_f32_dpp v229, v226, v64 row_ror:2 row_mask:0xf bank_mask:0xf
	v_fmac_f32_dpp v230, v227, v64 row_ror:2 row_mask:0xf bank_mask:0xf
	v_fmac_f32_dpp v231, v228, v64 row_ror:2 row_mask:0xf bank_mask:0xf
	v_fmac_f32_dpp v205, v236, v65 row_ror:2 row_mask:0xf bank_mask:0xf
	v_fmac_f32_dpp v196, v237, v65 row_ror:2 row_mask:0xf bank_mask:0xf
	v_fmac_f32_dpp v197, v238, v65 row_ror:2 row_mask:0xf bank_mask:0xf
	v_fmac_f32_dpp v176, v239, v65 row_ror:2 row_mask:0xf bank_mask:0xf
	v_exp_f32_e32 v221, v204
	v_exp_f32_e32 v222, v229
	v_exp_f32_e32 v223, v230
	v_exp_f32_e32 v224, v231
	v_exp_f32_e32 v232, v205
	v_exp_f32_e32 v233, v196
	v_exp_f32_e32 v234, v197
	v_exp_f32_e32 v235, v176
	v_fma_f32 v221, v221, s101, s101
	v_fma_f32 v222, v222, s101, s101
	v_fma_f32 v223, v223, s101, s101
	v_fma_f32 v224, v224, s101, s101
	v_fma_f32 v232, v232, s101, s101
	v_fma_f32 v233, v233, s101, s101
	v_fma_f32 v234, v234, s101, s101
	v_fma_f32 v235, v235, s101, s101
	v_rcp_f32_e32 v221, v221
	v_rcp_f32_e32 v222, v222
	v_rcp_f32_e32 v223, v223
	v_rcp_f32_e32 v224, v224
	v_rcp_f32_e32 v232, v232
	v_rcp_f32_e32 v233, v233
	v_rcp_f32_e32 v234, v234
	v_rcp_f32_e32 v235, v235
	v_mul_f32_e32 v221, v204, v221
	v_mul_f32_e32 v222, v229, v222
	v_mul_f32_e32 v223, v230, v223
	v_mul_f32_e32 v224, v231, v224
	v_mul_f32_e32 v232, v205, v232
	v_mul_f32_e32 v233, v196, v233
	v_mul_f32_e32 v234, v197, v234
	v_mul_f32_e32 v235, v176, v235
	v_mul_f32_e32 v240, v108, v244
	v_mul_f32_e32 v104, v104, v245
	v_mul_f32_e32 v100, v100, v246
	v_mul_f32_e32 v96, v96, v247
	v_mul_f32_e32 v241, v109, v244
	v_mul_f32_e32 v105, v105, v245
	v_mul_f32_e32 v101, v101, v246
	v_mul_f32_e32 v97, v97, v247
	v_mul_f32_e32 v108, v221, v240
	v_mul_f32_e32 v104, v222, v104
	v_mul_f32_e32 v100, v223, v100
	v_mul_f32_e32 v96, v224, v96
	v_mul_f32_e32 v109, v232, v241
	v_mul_f32_e32 v105, v233, v105
	v_mul_f32_e32 v101, v234, v101
	v_mul_f32_e32 v97, v235, v97
	v_cndmask_b32_e64 v221, v118, 0, s[36:37]
	v_cndmask_b32_e64 v225, v118, 0, s[44:45]
	v_cndmask_b32_e64 v222, v126, v118, s[36:37]
	v_cndmask_b32_e64 v226, v126, v118, s[44:45]
	v_cndmask_b32_e64 v223, v114, v126, s[36:37]
	v_cndmask_b32_e64 v227, v114, v126, s[44:45]
	v_cndmask_b32_e64 v224, v122, v114, s[36:37]
	v_cndmask_b32_e64 v228, v122, v114, s[44:45]
	v_cndmask_b32_e64 v232, v119, 0, s[36:37]
	v_cndmask_b32_e64 v236, v119, 0, s[44:45]
	v_cndmask_b32_e64 v233, v127, v119, s[36:37]
	v_cndmask_b32_e64 v237, v127, v119, s[44:45]
	v_cndmask_b32_e64 v234, v115, v127, s[36:37]
	v_cndmask_b32_e64 v238, v115, v127, s[44:45]
	v_cndmask_b32_e64 v235, v123, v115, s[36:37]
	v_cndmask_b32_e64 v239, v123, v115, s[44:45]
	v_fma_f32 v206, v78, v118, v70
	v_fma_f32 v229, v78, v126, v70
	v_fma_f32 v230, v78, v114, v70
	v_fma_f32 v231, v78, v122, v70
	v_fma_f32 v207, v79, v119, v71
	v_fma_f32 v196, v79, v127, v71
	v_fma_f32 v197, v79, v115, v71
	v_fma_f32 v176, v79, v123, v71
	v_fmac_f32_dpp v206, v221, v74 row_ror:1 row_mask:0xf bank_mask:0xf
	v_fmac_f32_dpp v229, v222, v74 row_ror:1 row_mask:0xf bank_mask:0xf
	v_fmac_f32_dpp v230, v223, v74 row_ror:1 row_mask:0xf bank_mask:0xf
	v_fmac_f32_dpp v231, v224, v74 row_ror:1 row_mask:0xf bank_mask:0xf
	v_fmac_f32_dpp v207, v232, v75 row_ror:1 row_mask:0xf bank_mask:0xf
	v_fmac_f32_dpp v196, v233, v75 row_ror:1 row_mask:0xf bank_mask:0xf
	v_fmac_f32_dpp v197, v234, v75 row_ror:1 row_mask:0xf bank_mask:0xf
	v_fmac_f32_dpp v176, v235, v75 row_ror:1 row_mask:0xf bank_mask:0xf
	v_fmac_f32_dpp v206, v225, v66 row_ror:2 row_mask:0xf bank_mask:0xf
	v_fmac_f32_dpp v229, v226, v66 row_ror:2 row_mask:0xf bank_mask:0xf
	v_fmac_f32_dpp v230, v227, v66 row_ror:2 row_mask:0xf bank_mask:0xf
	v_fmac_f32_dpp v231, v228, v66 row_ror:2 row_mask:0xf bank_mask:0xf
	v_fmac_f32_dpp v207, v236, v67 row_ror:2 row_mask:0xf bank_mask:0xf
	v_fmac_f32_dpp v196, v237, v67 row_ror:2 row_mask:0xf bank_mask:0xf
	v_fmac_f32_dpp v197, v238, v67 row_ror:2 row_mask:0xf bank_mask:0xf
	v_fmac_f32_dpp v176, v239, v67 row_ror:2 row_mask:0xf bank_mask:0xf
	v_exp_f32_e32 v221, v206
	v_exp_f32_e32 v222, v229
	v_exp_f32_e32 v223, v230
	v_exp_f32_e32 v224, v231
	v_exp_f32_e32 v232, v207
	v_exp_f32_e32 v233, v196
	v_exp_f32_e32 v234, v197
	v_exp_f32_e32 v235, v176
	v_fma_f32 v221, v221, s101, s101
	v_fma_f32 v222, v222, s101, s101
	v_fma_f32 v223, v223, s101, s101
	v_fma_f32 v224, v224, s101, s101
	v_fma_f32 v232, v232, s101, s101
	v_fma_f32 v233, v233, s101, s101
	v_fma_f32 v234, v234, s101, s101
	v_fma_f32 v235, v235, s101, s101
	v_rcp_f32_e32 v221, v221
	v_rcp_f32_e32 v222, v222
	v_rcp_f32_e32 v223, v223
	v_rcp_f32_e32 v224, v224
	v_rcp_f32_e32 v232, v232
	v_rcp_f32_e32 v233, v233
	v_rcp_f32_e32 v234, v234
	v_rcp_f32_e32 v235, v235
	v_mul_f32_e32 v221, v206, v221
	v_mul_f32_e32 v222, v229, v222
	v_mul_f32_e32 v223, v230, v223
	v_mul_f32_e32 v224, v231, v224
	v_mul_f32_e32 v232, v207, v232
	v_mul_f32_e32 v233, v196, v233
	v_mul_f32_e32 v234, v197, v234
	v_mul_f32_e32 v235, v176, v235
	v_mul_f32_e32 v242, v110, v244
	v_mul_f32_e32 v106, v106, v245
	v_mul_f32_e32 v102, v102, v246
	v_mul_f32_e32 v98, v98, v247
	v_mul_f32_e32 v243, v111, v244
	v_mul_f32_e32 v107, v107, v245
	v_mul_f32_e32 v103, v103, v246
	v_mul_f32_e32 v99, v99, v247
	v_mul_f32_e32 v110, v221, v242
	v_mul_f32_e32 v106, v222, v106
	v_mul_f32_e32 v102, v223, v102
	v_mul_f32_e32 v98, v224, v98
	v_mul_f32_e32 v111, v232, v243
	v_mul_f32_e32 v107, v233, v107
	v_mul_f32_e32 v103, v234, v103
	v_mul_f32_e32 v99, v235, v99
	v_cvt_pk_bf16_f32 v140, v140, v141
	v_cvt_pk_bf16_f32 v141, v142, v143
	v_cvt_pk_bf16_f32 v142, v108, v109
	v_cvt_pk_bf16_f32 v143, v110, v111
	v_cvt_pk_bf16_f32 v136, v136, v137
	v_cvt_pk_bf16_f32 v137, v138, v139
	v_cvt_pk_bf16_f32 v138, v104, v105
	v_cvt_pk_bf16_f32 v139, v106, v107
	v_cvt_pk_bf16_f32 v132, v132, v133
	v_cvt_pk_bf16_f32 v133, v134, v135
	v_cvt_pk_bf16_f32 v134, v100, v101
	v_cvt_pk_bf16_f32 v135, v102, v103
	v_cvt_pk_bf16_f32 v128, v128, v129
	v_cvt_pk_bf16_f32 v129, v130, v131
	v_cvt_pk_bf16_f32 v130, v96, v97
	v_cvt_pk_bf16_f32 v131, v98, v99
	v_mul_f32_e32 v200, 0xbf317218, v200
	v_mul_f32_e32 v201, 0xbf317218, v201
	v_mul_f32_e32 v202, 0xbf317218, v202
	v_mul_f32_e32 v203, 0xbf317218, v203
	v_mul_f32_e32 v204, 0xbf317218, v204
	v_mul_f32_e32 v205, 0xbf317218, v205
	v_mul_f32_e32 v206, 0xbf317218, v206
	v_mul_f32_e32 v207, 0xbf317218, v207
	v_or_b32_e32 v170, s11, v216
	v_mul_u32_u24_e32 v170, s10, v170
	v_lshl_add_u32 v170, v170, 2, v190
	s_and_saveexec_b64 s[0:1], s[42:43]
	global_store_dwordx4 v170, v[200:203], s[50:51]
	global_store_dwordx4 v170, v[204:207], s[50:51] offset:16
	global_store_dwordx4 v170, v[192:195], s[92:93]
	global_store_dwordx4 v170, v[240:243], s[92:93] offset:16
	s_or_b64 exec, exec, s[0:1]
	v_add_u32_e32 v171, s11, v218
	v_mul_u32_u24_e32 v171, s10, v171
	v_lshl_add_u32 v171, v171, 2, v190
	s_and_saveexec_b64 s[0:1], s[44:45]
	global_store_dwordx4 v171, v[150:153], s[52:53]
	global_store_dwordx4 v171, v[120:123], s[52:53] offset:16
	s_or_b64 exec, exec, s[0:1]
	v_mad_u32_u24 v172, v198, s20, v189
	s_and_saveexec_b64 s[0:1], s[40:41]
	global_store_dwordx4 v172, v[140:143], s[94:95]
	s_or_b64 exec, exec, s[0:1]
	v_add_u32_e32 v172, 0x16000, v172
	global_store_dwordx4 v172, v[136:139], s[94:95]
	v_add_u32_e32 v172, 0x16000, v172
	global_store_dwordx4 v172, v[132:135], s[94:95]
	v_add_u32_e32 v172, 0x16000, v172
	global_store_dwordx4 v172, v[128:131], s[94:95]
	s_add_i32 s11, s11, 4
	v_cndmask_b32_e64 v221, v48, 0, s[36:37]
	v_cndmask_b32_e64 v225, v48, 0, s[44:45]
	v_cndmask_b32_e64 v222, v60, v48, s[36:37]
	v_cndmask_b32_e64 v226, v60, v48, s[44:45]
	v_cndmask_b32_e64 v223, v56, v60, s[36:37]
	v_cndmask_b32_e64 v227, v56, v60, s[44:45]
	v_cndmask_b32_e64 v224, v52, v56, s[36:37]
	v_cndmask_b32_e64 v228, v52, v56, s[44:45]
	v_cndmask_b32_e64 v232, v49, 0, s[36:37]
	v_cndmask_b32_e64 v236, v49, 0, s[44:45]
	v_cndmask_b32_e64 v233, v61, v49, s[36:37]
	v_cndmask_b32_e64 v237, v61, v49, s[44:45]
	v_cndmask_b32_e64 v234, v57, v61, s[36:37]
	v_cndmask_b32_e64 v238, v57, v61, s[44:45]
	v_cndmask_b32_e64 v235, v53, v57, s[36:37]
	v_cndmask_b32_e64 v239, v53, v57, s[44:45]
	v_fma_f32 v200, v92, v48, v84
	v_fma_f32 v229, v92, v60, v84
	v_fma_f32 v230, v92, v56, v84
	v_fma_f32 v231, v92, v52, v84
	v_fma_f32 v201, v93, v49, v85
	v_fma_f32 v196, v93, v61, v85
	v_fma_f32 v197, v93, v57, v85
	v_fma_f32 v176, v93, v53, v85
	v_fmac_f32_dpp v200, v221, v88 row_ror:1 row_mask:0xf bank_mask:0xf
	v_fmac_f32_dpp v229, v222, v88 row_ror:1 row_mask:0xf bank_mask:0xf
	v_fmac_f32_dpp v230, v223, v88 row_ror:1 row_mask:0xf bank_mask:0xf
	v_fmac_f32_dpp v231, v224, v88 row_ror:1 row_mask:0xf bank_mask:0xf
	v_fmac_f32_dpp v201, v232, v89 row_ror:1 row_mask:0xf bank_mask:0xf
	v_fmac_f32_dpp v196, v233, v89 row_ror:1 row_mask:0xf bank_mask:0xf
	v_fmac_f32_dpp v197, v234, v89 row_ror:1 row_mask:0xf bank_mask:0xf
	v_fmac_f32_dpp v176, v235, v89 row_ror:1 row_mask:0xf bank_mask:0xf
	v_fmac_f32_dpp v200, v225, v80 row_ror:2 row_mask:0xf bank_mask:0xf
	v_fmac_f32_dpp v229, v226, v80 row_ror:2 row_mask:0xf bank_mask:0xf
	v_fmac_f32_dpp v230, v227, v80 row_ror:2 row_mask:0xf bank_mask:0xf
	v_fmac_f32_dpp v231, v228, v80 row_ror:2 row_mask:0xf bank_mask:0xf
	v_fmac_f32_dpp v201, v236, v81 row_ror:2 row_mask:0xf bank_mask:0xf
	v_fmac_f32_dpp v196, v237, v81 row_ror:2 row_mask:0xf bank_mask:0xf
	v_fmac_f32_dpp v197, v238, v81 row_ror:2 row_mask:0xf bank_mask:0xf
	v_fmac_f32_dpp v176, v239, v81 row_ror:2 row_mask:0xf bank_mask:0xf
	v_exp_f32_e32 v221, v200
	v_exp_f32_e32 v222, v229
	v_exp_f32_e32 v223, v230
	v_exp_f32_e32 v224, v231
	v_exp_f32_e32 v232, v201
	v_exp_f32_e32 v233, v196
	v_exp_f32_e32 v234, v197
	v_exp_f32_e32 v235, v176
	v_fma_f32 v221, v221, s101, s101
	v_fma_f32 v222, v222, s101, s101
	v_fma_f32 v223, v223, s101, s101
	v_fma_f32 v224, v224, s101, s101
	v_fma_f32 v232, v232, s101, s101
	v_fma_f32 v233, v233, s101, s101
	v_fma_f32 v234, v234, s101, s101
	v_fma_f32 v235, v235, s101, s101
	v_rcp_f32_e32 v221, v221
	v_rcp_f32_e32 v222, v222
	v_rcp_f32_e32 v223, v223
	v_rcp_f32_e32 v224, v224
	v_rcp_f32_e32 v232, v232
	v_rcp_f32_e32 v233, v233
	v_rcp_f32_e32 v234, v234
	v_rcp_f32_e32 v235, v235
	v_mul_f32_e32 v221, v200, v221
	v_mul_f32_e32 v222, v229, v222
	v_mul_f32_e32 v223, v230, v223
	v_mul_f32_e32 v224, v231, v224
	v_mul_f32_e32 v232, v201, v232
	v_mul_f32_e32 v233, v196, v233
	v_mul_f32_e32 v234, v197, v234
	v_mul_f32_e32 v235, v176, v235
	v_mul_f32_e32 v192, v44, v248
	v_mul_f32_e32 v40, v40, v249
	v_mul_f32_e32 v36, v36, v250
	v_mul_f32_e32 v32, v32, v251
	v_mul_f32_e32 v193, v45, v248
	v_mul_f32_e32 v41, v41, v249
	v_mul_f32_e32 v37, v37, v250
	v_mul_f32_e32 v33, v33, v251
	v_mul_f32_e32 v44, v221, v192
	v_mul_f32_e32 v40, v222, v40
	v_mul_f32_e32 v36, v223, v36
	v_mul_f32_e32 v32, v224, v32
	v_mul_f32_e32 v45, v232, v193
	v_mul_f32_e32 v41, v233, v41
	v_mul_f32_e32 v37, v234, v37
	v_mul_f32_e32 v33, v235, v33
	v_cndmask_b32_e64 v221, v50, 0, s[36:37]
	v_cndmask_b32_e64 v225, v50, 0, s[44:45]
	v_cndmask_b32_e64 v222, v62, v50, s[36:37]
	v_cndmask_b32_e64 v226, v62, v50, s[44:45]
	v_cndmask_b32_e64 v223, v58, v62, s[36:37]
	v_cndmask_b32_e64 v227, v58, v62, s[44:45]
	v_cndmask_b32_e64 v224, v54, v58, s[36:37]
	v_cndmask_b32_e64 v228, v54, v58, s[44:45]
	v_cndmask_b32_e64 v232, v51, 0, s[36:37]
	v_cndmask_b32_e64 v236, v51, 0, s[44:45]
	v_cndmask_b32_e64 v233, v63, v51, s[36:37]
	v_cndmask_b32_e64 v237, v63, v51, s[44:45]
	v_cndmask_b32_e64 v234, v59, v63, s[36:37]
	v_cndmask_b32_e64 v238, v59, v63, s[44:45]
	v_cndmask_b32_e64 v235, v55, v59, s[36:37]
	v_cndmask_b32_e64 v239, v55, v59, s[44:45]
	v_fma_f32 v202, v94, v50, v86
	v_fma_f32 v229, v94, v62, v86
	v_fma_f32 v230, v94, v58, v86
	v_fma_f32 v231, v94, v54, v86
	v_fma_f32 v203, v95, v51, v87
	v_fma_f32 v196, v95, v63, v87
	v_fma_f32 v197, v95, v59, v87
	v_fma_f32 v176, v95, v55, v87
	v_fmac_f32_dpp v202, v221, v90 row_ror:1 row_mask:0xf bank_mask:0xf
	v_fmac_f32_dpp v229, v222, v90 row_ror:1 row_mask:0xf bank_mask:0xf
	v_fmac_f32_dpp v230, v223, v90 row_ror:1 row_mask:0xf bank_mask:0xf
	v_fmac_f32_dpp v231, v224, v90 row_ror:1 row_mask:0xf bank_mask:0xf
	v_fmac_f32_dpp v203, v232, v91 row_ror:1 row_mask:0xf bank_mask:0xf
	v_fmac_f32_dpp v196, v233, v91 row_ror:1 row_mask:0xf bank_mask:0xf
	v_fmac_f32_dpp v197, v234, v91 row_ror:1 row_mask:0xf bank_mask:0xf
	v_fmac_f32_dpp v176, v235, v91 row_ror:1 row_mask:0xf bank_mask:0xf
	v_fmac_f32_dpp v202, v225, v82 row_ror:2 row_mask:0xf bank_mask:0xf
	v_fmac_f32_dpp v229, v226, v82 row_ror:2 row_mask:0xf bank_mask:0xf
	v_fmac_f32_dpp v230, v227, v82 row_ror:2 row_mask:0xf bank_mask:0xf
	v_fmac_f32_dpp v231, v228, v82 row_ror:2 row_mask:0xf bank_mask:0xf
	v_fmac_f32_dpp v203, v236, v83 row_ror:2 row_mask:0xf bank_mask:0xf
	v_fmac_f32_dpp v196, v237, v83 row_ror:2 row_mask:0xf bank_mask:0xf
	v_fmac_f32_dpp v197, v238, v83 row_ror:2 row_mask:0xf bank_mask:0xf
	v_fmac_f32_dpp v176, v239, v83 row_ror:2 row_mask:0xf bank_mask:0xf
	v_exp_f32_e32 v221, v202
	v_exp_f32_e32 v222, v229
	v_exp_f32_e32 v223, v230
	v_exp_f32_e32 v224, v231
	v_exp_f32_e32 v232, v203
	v_exp_f32_e32 v233, v196
	v_exp_f32_e32 v234, v197
	v_exp_f32_e32 v235, v176
	v_fma_f32 v221, v221, s101, s101
	v_fma_f32 v222, v222, s101, s101
	v_fma_f32 v223, v223, s101, s101
	v_fma_f32 v224, v224, s101, s101
	v_fma_f32 v232, v232, s101, s101
	v_fma_f32 v233, v233, s101, s101
	v_fma_f32 v234, v234, s101, s101
	v_fma_f32 v235, v235, s101, s101
	v_rcp_f32_e32 v221, v221
	v_rcp_f32_e32 v222, v222
	v_rcp_f32_e32 v223, v223
	v_rcp_f32_e32 v224, v224
	v_rcp_f32_e32 v232, v232
	v_rcp_f32_e32 v233, v233
	v_rcp_f32_e32 v234, v234
	v_rcp_f32_e32 v235, v235
	v_mul_f32_e32 v221, v202, v221
	v_mul_f32_e32 v222, v229, v222
	v_mul_f32_e32 v223, v230, v223
	v_mul_f32_e32 v224, v231, v224
	v_mul_f32_e32 v232, v203, v232
	v_mul_f32_e32 v233, v196, v233
	v_mul_f32_e32 v234, v197, v234
	v_mul_f32_e32 v235, v176, v235
	v_mul_f32_e32 v194, v46, v248
	v_mul_f32_e32 v42, v42, v249
	v_mul_f32_e32 v38, v38, v250
	v_mul_f32_e32 v34, v34, v251
	v_mul_f32_e32 v195, v47, v248
	v_mul_f32_e32 v43, v43, v249
	v_mul_f32_e32 v39, v39, v250
	v_mul_f32_e32 v35, v35, v251
	v_mul_f32_e32 v46, v221, v194
	v_mul_f32_e32 v42, v222, v42
	v_mul_f32_e32 v38, v223, v38
	v_mul_f32_e32 v34, v224, v34
	v_mul_f32_e32 v47, v232, v195
	v_mul_f32_e32 v43, v233, v43
	v_mul_f32_e32 v39, v234, v39
	v_mul_f32_e32 v35, v235, v35
	v_cndmask_b32_e64 v221, v20, 0, s[36:37]
	v_cndmask_b32_e64 v225, v20, 0, s[44:45]
	v_cndmask_b32_e64 v222, v28, v20, s[36:37]
	v_cndmask_b32_e64 v226, v28, v20, s[44:45]
	v_cndmask_b32_e64 v223, v16, v28, s[36:37]
	v_cndmask_b32_e64 v227, v16, v28, s[44:45]
	v_cndmask_b32_e64 v224, v24, v16, s[36:37]
	v_cndmask_b32_e64 v228, v24, v16, s[44:45]
	v_cndmask_b32_e64 v232, v21, 0, s[36:37]
	v_cndmask_b32_e64 v236, v21, 0, s[44:45]
	v_cndmask_b32_e64 v233, v29, v21, s[36:37]
	v_cndmask_b32_e64 v237, v29, v21, s[44:45]
	v_cndmask_b32_e64 v234, v17, v29, s[36:37]
	v_cndmask_b32_e64 v238, v17, v29, s[44:45]
	v_cndmask_b32_e64 v235, v25, v17, s[36:37]
	v_cndmask_b32_e64 v239, v25, v17, s[44:45]
	v_fma_f32 v204, v76, v20, v68
	v_fma_f32 v229, v76, v28, v68
	v_fma_f32 v230, v76, v16, v68
	v_fma_f32 v231, v76, v24, v68
	v_fma_f32 v205, v77, v21, v69
	v_fma_f32 v196, v77, v29, v69
	v_fma_f32 v197, v77, v17, v69
	v_fma_f32 v176, v77, v25, v69
	v_fmac_f32_dpp v204, v221, v72 row_ror:1 row_mask:0xf bank_mask:0xf
	v_fmac_f32_dpp v229, v222, v72 row_ror:1 row_mask:0xf bank_mask:0xf
	v_fmac_f32_dpp v230, v223, v72 row_ror:1 row_mask:0xf bank_mask:0xf
	v_fmac_f32_dpp v231, v224, v72 row_ror:1 row_mask:0xf bank_mask:0xf
	v_fmac_f32_dpp v205, v232, v73 row_ror:1 row_mask:0xf bank_mask:0xf
	v_fmac_f32_dpp v196, v233, v73 row_ror:1 row_mask:0xf bank_mask:0xf
	v_fmac_f32_dpp v197, v234, v73 row_ror:1 row_mask:0xf bank_mask:0xf
	v_fmac_f32_dpp v176, v235, v73 row_ror:1 row_mask:0xf bank_mask:0xf
	v_fmac_f32_dpp v204, v225, v64 row_ror:2 row_mask:0xf bank_mask:0xf
	v_fmac_f32_dpp v229, v226, v64 row_ror:2 row_mask:0xf bank_mask:0xf
	v_fmac_f32_dpp v230, v227, v64 row_ror:2 row_mask:0xf bank_mask:0xf
	v_fmac_f32_dpp v231, v228, v64 row_ror:2 row_mask:0xf bank_mask:0xf
	v_fmac_f32_dpp v205, v236, v65 row_ror:2 row_mask:0xf bank_mask:0xf
	v_fmac_f32_dpp v196, v237, v65 row_ror:2 row_mask:0xf bank_mask:0xf
	v_fmac_f32_dpp v197, v238, v65 row_ror:2 row_mask:0xf bank_mask:0xf
	v_fmac_f32_dpp v176, v239, v65 row_ror:2 row_mask:0xf bank_mask:0xf
	v_exp_f32_e32 v221, v204
	v_exp_f32_e32 v222, v229
	v_exp_f32_e32 v223, v230
	v_exp_f32_e32 v224, v231
	v_exp_f32_e32 v232, v205
	v_exp_f32_e32 v233, v196
	v_exp_f32_e32 v234, v197
	v_exp_f32_e32 v235, v176
	v_fma_f32 v221, v221, s101, s101
	v_fma_f32 v222, v222, s101, s101
	v_fma_f32 v223, v223, s101, s101
	v_fma_f32 v224, v224, s101, s101
	v_fma_f32 v232, v232, s101, s101
	v_fma_f32 v233, v233, s101, s101
	v_fma_f32 v234, v234, s101, s101
	v_fma_f32 v235, v235, s101, s101
	v_rcp_f32_e32 v221, v221
	v_rcp_f32_e32 v222, v222
	v_rcp_f32_e32 v223, v223
	v_rcp_f32_e32 v224, v224
	v_rcp_f32_e32 v232, v232
	v_rcp_f32_e32 v233, v233
	v_rcp_f32_e32 v234, v234
	v_rcp_f32_e32 v235, v235
	v_mul_f32_e32 v221, v204, v221
	v_mul_f32_e32 v222, v229, v222
	v_mul_f32_e32 v223, v230, v223
	v_mul_f32_e32 v224, v231, v224
	v_mul_f32_e32 v232, v205, v232
	v_mul_f32_e32 v233, v196, v233
	v_mul_f32_e32 v234, v197, v234
	v_mul_f32_e32 v235, v176, v235
	v_mul_f32_e32 v240, v12, v248
	v_mul_f32_e32 v8, v8, v249
	v_mul_f32_e32 v4, v4, v250
	v_mul_f32_e32 v0, v0, v251
	v_mul_f32_e32 v241, v13, v248
	v_mul_f32_e32 v9, v9, v249
	v_mul_f32_e32 v5, v5, v250
	v_mul_f32_e32 v1, v1, v251
	v_mul_f32_e32 v12, v221, v240
	v_mul_f32_e32 v8, v222, v8
	v_mul_f32_e32 v4, v223, v4
	v_mul_f32_e32 v0, v224, v0
	v_mul_f32_e32 v13, v232, v241
	v_mul_f32_e32 v9, v233, v9
	v_mul_f32_e32 v5, v234, v5
	v_mul_f32_e32 v1, v235, v1
	v_cndmask_b32_e64 v221, v22, 0, s[36:37]
	v_cndmask_b32_e64 v225, v22, 0, s[44:45]
	v_cndmask_b32_e64 v222, v30, v22, s[36:37]
	v_cndmask_b32_e64 v226, v30, v22, s[44:45]
	v_cndmask_b32_e64 v223, v18, v30, s[36:37]
	v_cndmask_b32_e64 v227, v18, v30, s[44:45]
	v_cndmask_b32_e64 v224, v26, v18, s[36:37]
	v_cndmask_b32_e64 v228, v26, v18, s[44:45]
	v_cndmask_b32_e64 v232, v23, 0, s[36:37]
	v_cndmask_b32_e64 v236, v23, 0, s[44:45]
	v_cndmask_b32_e64 v233, v31, v23, s[36:37]
	v_cndmask_b32_e64 v237, v31, v23, s[44:45]
	v_cndmask_b32_e64 v234, v19, v31, s[36:37]
	v_cndmask_b32_e64 v238, v19, v31, s[44:45]
	v_cndmask_b32_e64 v235, v27, v19, s[36:37]
	v_cndmask_b32_e64 v239, v27, v19, s[44:45]
	v_fma_f32 v206, v78, v22, v70
	v_fma_f32 v229, v78, v30, v70
	v_fma_f32 v230, v78, v18, v70
	v_fma_f32 v231, v78, v26, v70
	v_fma_f32 v207, v79, v23, v71
	v_fma_f32 v196, v79, v31, v71
	v_fma_f32 v197, v79, v19, v71
	v_fma_f32 v176, v79, v27, v71
	v_fmac_f32_dpp v206, v221, v74 row_ror:1 row_mask:0xf bank_mask:0xf
	v_fmac_f32_dpp v229, v222, v74 row_ror:1 row_mask:0xf bank_mask:0xf
	v_fmac_f32_dpp v230, v223, v74 row_ror:1 row_mask:0xf bank_mask:0xf
	v_fmac_f32_dpp v231, v224, v74 row_ror:1 row_mask:0xf bank_mask:0xf
	v_fmac_f32_dpp v207, v232, v75 row_ror:1 row_mask:0xf bank_mask:0xf
	v_fmac_f32_dpp v196, v233, v75 row_ror:1 row_mask:0xf bank_mask:0xf
	v_fmac_f32_dpp v197, v234, v75 row_ror:1 row_mask:0xf bank_mask:0xf
	v_fmac_f32_dpp v176, v235, v75 row_ror:1 row_mask:0xf bank_mask:0xf
	v_fmac_f32_dpp v206, v225, v66 row_ror:2 row_mask:0xf bank_mask:0xf
	v_fmac_f32_dpp v229, v226, v66 row_ror:2 row_mask:0xf bank_mask:0xf
	v_fmac_f32_dpp v230, v227, v66 row_ror:2 row_mask:0xf bank_mask:0xf
	v_fmac_f32_dpp v231, v228, v66 row_ror:2 row_mask:0xf bank_mask:0xf
	v_fmac_f32_dpp v207, v236, v67 row_ror:2 row_mask:0xf bank_mask:0xf
	v_fmac_f32_dpp v196, v237, v67 row_ror:2 row_mask:0xf bank_mask:0xf
	v_fmac_f32_dpp v197, v238, v67 row_ror:2 row_mask:0xf bank_mask:0xf
	v_fmac_f32_dpp v176, v239, v67 row_ror:2 row_mask:0xf bank_mask:0xf
	v_exp_f32_e32 v221, v206
	v_exp_f32_e32 v222, v229
	v_exp_f32_e32 v223, v230
	v_exp_f32_e32 v224, v231
	v_exp_f32_e32 v232, v207
	v_exp_f32_e32 v233, v196
	v_exp_f32_e32 v234, v197
	v_exp_f32_e32 v235, v176
	v_fma_f32 v221, v221, s101, s101
	v_fma_f32 v222, v222, s101, s101
	v_fma_f32 v223, v223, s101, s101
	v_fma_f32 v224, v224, s101, s101
	v_fma_f32 v232, v232, s101, s101
	v_fma_f32 v233, v233, s101, s101
	v_fma_f32 v234, v234, s101, s101
	v_fma_f32 v235, v235, s101, s101
	v_rcp_f32_e32 v221, v221
	v_rcp_f32_e32 v222, v222
	v_rcp_f32_e32 v223, v223
	v_rcp_f32_e32 v224, v224
	v_rcp_f32_e32 v232, v232
	v_rcp_f32_e32 v233, v233
	v_rcp_f32_e32 v234, v234
	v_rcp_f32_e32 v235, v235
	v_mul_f32_e32 v221, v206, v221
	v_mul_f32_e32 v222, v229, v222
	v_mul_f32_e32 v223, v230, v223
	v_mul_f32_e32 v224, v231, v224
	v_mul_f32_e32 v232, v207, v232
	v_mul_f32_e32 v233, v196, v233
	v_mul_f32_e32 v234, v197, v234
	v_mul_f32_e32 v235, v176, v235
	v_mul_f32_e32 v242, v14, v248
	v_mul_f32_e32 v10, v10, v249
	v_mul_f32_e32 v6, v6, v250
	v_mul_f32_e32 v2, v2, v251
	v_mul_f32_e32 v243, v15, v248
	v_mul_f32_e32 v11, v11, v249
	v_mul_f32_e32 v7, v7, v250
	v_mul_f32_e32 v3, v3, v251
	v_mul_f32_e32 v14, v221, v242
	v_mul_f32_e32 v10, v222, v10
	v_mul_f32_e32 v6, v223, v6
	v_mul_f32_e32 v2, v224, v2
	v_mul_f32_e32 v15, v232, v243
	v_mul_f32_e32 v11, v233, v11
	v_mul_f32_e32 v7, v234, v7
	v_mul_f32_e32 v3, v235, v3
	v_cvt_pk_bf16_f32 v44, v44, v45
	v_cvt_pk_bf16_f32 v45, v46, v47
	v_cvt_pk_bf16_f32 v46, v12, v13
	v_cvt_pk_bf16_f32 v47, v14, v15
	v_cvt_pk_bf16_f32 v40, v40, v41
	v_cvt_pk_bf16_f32 v41, v42, v43
	v_cvt_pk_bf16_f32 v42, v8, v9
	v_cvt_pk_bf16_f32 v43, v10, v11
	v_cvt_pk_bf16_f32 v36, v36, v37
	v_cvt_pk_bf16_f32 v37, v38, v39
	v_cvt_pk_bf16_f32 v38, v4, v5
	v_cvt_pk_bf16_f32 v39, v6, v7
	v_cvt_pk_bf16_f32 v32, v32, v33
	v_cvt_pk_bf16_f32 v33, v34, v35
	v_cvt_pk_bf16_f32 v34, v0, v1
	v_cvt_pk_bf16_f32 v35, v2, v3
	v_mul_f32_e32 v200, 0xbf317218, v200
	v_mul_f32_e32 v201, 0xbf317218, v201
	v_mul_f32_e32 v202, 0xbf317218, v202
	v_mul_f32_e32 v203, 0xbf317218, v203
	v_mul_f32_e32 v204, 0xbf317218, v204
	v_mul_f32_e32 v205, 0xbf317218, v205
	v_mul_f32_e32 v206, 0xbf317218, v206
	v_mul_f32_e32 v207, 0xbf317218, v207
	v_or_b32_e32 v170, s11, v216
	v_mul_u32_u24_e32 v170, s10, v170
	v_lshl_add_u32 v170, v170, 2, v190
	s_and_saveexec_b64 s[0:1], s[42:43]
	global_store_dwordx4 v170, v[200:203], s[50:51]
	global_store_dwordx4 v170, v[204:207], s[50:51] offset:16
	global_store_dwordx4 v170, v[192:195], s[92:93]
	global_store_dwordx4 v170, v[240:243], s[92:93] offset:16
	s_or_b64 exec, exec, s[0:1]
	v_add_u32_e32 v171, s11, v218
	v_mul_u32_u24_e32 v171, s10, v171
	v_lshl_add_u32 v171, v171, 2, v190
	s_and_saveexec_b64 s[0:1], s[44:45]
	global_store_dwordx4 v171, v[52:55], s[52:53]
	global_store_dwordx4 v171, v[24:27], s[52:53] offset:16
	s_or_b64 exec, exec, s[0:1]
	v_mad_u32_u24 v172, v168, s20, v189
	s_and_saveexec_b64 s[0:1], s[40:41]
	global_store_dwordx4 v172, v[44:47], s[94:95]
	s_or_b64 exec, exec, s[0:1]
	v_add_u32_e32 v172, 0x16000, v172
	global_store_dwordx4 v172, v[40:43], s[94:95]
	v_add_u32_e32 v172, 0x16000, v172
	global_store_dwordx4 v172, v[36:39], s[94:95]
	v_add_u32_e32 v172, 0x16000, v172
	global_store_dwordx4 v172, v[32:35], s[94:95]
	s_and_b64 vcc, exec, s[46:47]
	s_mov_b32 s0, s76
	s_mov_b32 s84, s78
	s_mov_b64 s[82:83], s[72:73]
	s_mov_b64 s[86:87], s[80:81]
	s_cbranch_vccnz .LBB0_146
	s_branch .LBB0_122

	.amdhsa_kernel _Z5k_run7MParams
		.amdhsa_group_segment_fixed_size 0
		.amdhsa_private_segment_fixed_size 0
		.amdhsa_kernarg_size 448
		.amdhsa_user_sgpr_count 2
		.amdhsa_user_sgpr_dispatch_ptr 0
		.amdhsa_user_sgpr_queue_ptr 0
		.amdhsa_user_sgpr_kernarg_segment_ptr 1
		.amdhsa_user_sgpr_dispatch_id 0
		.amdhsa_user_sgpr_kernarg_preload_length 0
		.amdhsa_user_sgpr_kernarg_preload_offset 0
		.amdhsa_user_sgpr_private_segment_size 0
		.amdhsa_uses_dynamic_stack 0
		.amdhsa_enable_private_segment 0
		.amdhsa_system_sgpr_workgroup_id_x 1
		.amdhsa_system_sgpr_workgroup_id_y 0
		.amdhsa_system_sgpr_workgroup_id_z 0
		.amdhsa_system_sgpr_workgroup_info 0
		.amdhsa_system_vgpr_workitem_id 2
		.amdhsa_next_free_vgpr 256
		.amdhsa_next_free_sgpr 102
		.amdhsa_accum_offset 256
		.amdhsa_reserve_vcc 1
		.amdhsa_float_round_mode_32 0
		.amdhsa_float_round_mode_16_64 0
		.amdhsa_float_denorm_mode_32 3
		.amdhsa_float_denorm_mode_16_64 3
		.amdhsa_dx10_clamp 1
		.amdhsa_ieee_mode 1
		.amdhsa_fp16_overflow 0
		.amdhsa_tg_split 0
		.amdhsa_exception_fp_ieee_invalid_op 0
		.amdhsa_exception_fp_denorm_src 0
		.amdhsa_exception_fp_ieee_div_zero 0
		.amdhsa_exception_fp_ieee_overflow 0
		.amdhsa_exception_fp_ieee_underflow 0
		.amdhsa_exception_fp_ieee_inexact 0
		.amdhsa_exception_int_div_zero 0
	.end_amdhsa_kernel

amdhsa.kernels:
  - .agpr_count:     0
    .args:
      - .offset:         0
        .size:           192
        .value_kind:     by_value
      - .offset:         192
        .size:           4
        .value_kind:     hidden_block_count_x
      - .offset:         196
        .size:           4
        .value_kind:     hidden_block_count_y
      - .offset:         200
        .size:           4
        .value_kind:     hidden_block_count_z
      - .offset:         204
        .size:           2
        .value_kind:     hidden_group_size_x
      - .offset:         206
        .size:           2
        .value_kind:     hidden_group_size_y
      - .offset:         208
        .size:           2
        .value_kind:     hidden_group_size_z
      - .offset:         210
        .size:           2
        .value_kind:     hidden_remainder_x
      - .offset:         212
        .size:           2
        .value_kind:     hidden_remainder_y
      - .offset:         214
        .size:           2
        .value_kind:     hidden_remainder_z
      - .offset:         232
        .size:           8
        .value_kind:     hidden_global_offset_x
      - .offset:         240
        .size:           8
        .value_kind:     hidden_global_offset_y
      - .offset:         248
        .size:           8
        .value_kind:     hidden_global_offset_z
      - .offset:         256
        .size:           2
        .value_kind:     hidden_grid_dims
      - .offset:         280
        .size:           8
        .value_kind:     hidden_multigrid_sync_arg
      - .offset:         312
        .size:           4
        .value_kind:     hidden_dynamic_lds_size
    .group_segment_fixed_size: 0
    .kernarg_segment_align: 8
    .kernarg_segment_size: 448
    .language:       OpenCL C
    .language_version:
      - 2
      - 0
    .max_flat_workgroup_size: 512
    .name:           _Z5k_run7MParams
    .private_segment_fixed_size: 0
    .sgpr_count:     108
    .sgpr_spill_count: 212
    .symbol:         _Z5k_run7MParams.kd
    .uniform_work_group_size: 1
    .uses_dynamic_stack: false
    .vgpr_count:     256
    .vgpr_spill_count: 0
    .wavefront_size: 64
